# step 2 l2norm: 16 row sums by one merged butterfly (rows packed by lane bits, two crossbar steps) instead of 16 DPP ladders; rsqrt and q scale once for all rows
# baseline (speedup 1.0000x reference)
.LBB0_133:
	s_or_b64 exec, exec, s[28:29]
	s_add_i32 s47, s50, s5
	s_cmpk_gt_i32 s47, 0x7ff
	s_cselect_b64 s[44:45], -1, 0
	s_lshl_b32 s6, s47, 6
	s_and_b32 s6, s6, 0x7c0
	s_ashr_i32 s7, s47, 5
	s_or_b32 s6, s6, s7
	s_cmpk_lt_i32 s47, 0x800
	s_cselect_b32 s7, s6, s42
	s_and_b32 s10, s7, 63
	s_lshl_b32 s6, s7, 4
	s_lshl_b32 s8, s7, 2
	s_and_b32 s6, s6, 0xfffff000
	s_lshl_b32 s11, s10, 6
	s_and_b32 s8, s8, 0x300
	s_add_u32 s8, s88, s8
	s_addc_u32 s9, s89, 0
	s_cmp_lg_u32 s10, 0
	s_cselect_b64 s[28:29], -1, 0
	s_or_b32 s10, s11, s6
	s_add_i32 s10, s10, -3
	s_mul_i32 s11, s10, 0x1800
	s_mul_hi_i32 s34, s10, 0x1800
	s_add_u32 s8, s8, s11
	s_addc_u32 s9, s9, s34
	v_cmp_eq_u32_e64 s[56:57], v132, v139
	v_cmp_eq_u32_e64 s[58:59], v133, v140
	v_cmp_eq_u32_e64 s[60:61], v134, v141
	v_cmp_eq_u32_e64 s[62:63], v135, v142
	v_cmp_eq_u32_e64 s[64:65], v136, v143
	v_cmp_eq_u32_e64 s[66:67], v137, v144
	v_cmp_eq_u32_e64 s[68:69], v138, v145
	s_or_b64 s[56:57], s[56:57], s[28:29]
	s_or_b64 s[58:59], s[58:59], s[28:29]
	s_or_b64 s[60:61], s[60:61], s[28:29]
	s_or_b64 s[62:63], s[62:63], s[28:29]
	s_or_b64 s[64:65], s[64:65], s[28:29]
	s_or_b64 s[66:67], s[66:67], s[28:29]
	s_or_b64 s[68:69], s[68:69], s[28:29]
	v_cndmask_b32_e64 v2, v139, v132, s[56:57]
	v_cndmask_b32_e64 v3, v140, v133, s[58:59]
	v_cndmask_b32_e64 v4, v141, v134, s[60:61]
	v_cndmask_b32_e64 v5, v142, v135, s[62:63]
	v_cndmask_b32_e64 v6, v143, v136, s[64:65]
	v_cndmask_b32_e64 v7, v144, v137, s[66:67]
	v_cndmask_b32_e64 v8, v145, v138, s[68:69]
	global_load_dwordx4 v[38:41], v2, s[8:9]
	global_load_dwordx4 v[34:37], v3, s[8:9]
	global_load_dwordx4 v[46:49], v4, s[8:9]
	global_load_dwordx4 v[42:45], v5, s[8:9]
	global_load_dwordx4 v[54:57], v6, s[8:9]
	global_load_dwordx4 v[50:53], v7, s[8:9]
	global_load_dwordx4 v[58:61], v8, s[8:9]
	s_bfe_u32 s28, s7, 0x20006
	s_lshl_b32 s34, s28, 9
	v_lshl_add_u64 v[2:3], v[70:71], 0, s[34:35]
	v_add_co_u32_e32 v4, vcc, s90, v2
	s_movk_i32 s8, 0x3000
	s_nop 0
	v_addc_co_u32_e32 v5, vcc, 0, v3, vcc
	v_add_co_u32_e32 v6, vcc, s8, v2
	s_movk_i32 s8, 0x2000
	s_nop 0
	v_addc_co_u32_e32 v7, vcc, 0, v3, vcc
	v_add_co_u32_e32 v8, vcc, s97, v2
	s_lshl_b32 s7, s7, 6
	s_nop 0
	v_addc_co_u32_e32 v9, vcc, 0, v3, vcc
	v_add_co_u32_e32 v10, vcc, s8, v2
	s_movk_i32 s8, 0x5000
	s_nop 0
	v_addc_co_u32_e32 v11, vcc, 0, v3, vcc
	s_and_b32 s7, s7, 0xfc0
	v_add_co_u32_e32 v12, vcc, s8, v2
	s_lshl_b32 s34, s28, 2
	s_nop 0
	v_addc_co_u32_e32 v13, vcc, 0, v3, vcc
	global_load_dwordx2 v[74:75], v[10:11], off
	global_load_dwordx2 v[76:77], v[12:13], off
	global_load_dwordx2 v[64:65], v[10:11], off offset:2048
	global_load_dwordx2 v[78:79], v[6:7], off offset:2048
	global_load_dwordx2 v[86:87], v[2:3], off
	global_load_dwordx2 v[84:85], v[4:5], off offset:2048
	global_load_dwordx2 v[72:73], v[2:3], off offset:2048
	global_load_dwordx2 v[66:67], v[4:5], off
	global_load_dwordx2 v[80:81], v[8:9], off offset:-4096
	global_load_dwordx2 v[82:83], v[8:9], off offset:2048
	global_load_dwordx2 v[62:63], v[8:9], off
	global_load_dwordx2 v[68:69], v[12:13], off offset:2048
	v_or_b32_e32 v2, s7, v224
	v_or_b32_e32 v2, s6, v2
	v_ashrrev_i32_e32 v3, 31, v2
	v_readlane_b32 s6, v254, 22
	s_load_dwordx4 s[8:11], s[0:1], 0x60
	v_lshlrev_b64 v[2:3], 5, v[2:3]
	v_readlane_b32 s7, v254, 23
	s_nop 1
	v_lshl_add_u64 v[2:3], s[6:7], 0, v[2:3]
	s_or_b32 s6, s28, s18
	s_ashr_i32 s7, s6, 31
	s_lshl_b64 s[6:7], s[6:7], 2
	s_waitcnt lgkmcnt(0)
	s_add_u32 s10, s10, s6
	s_addc_u32 s11, s11, s7
	s_add_u32 s6, s8, s6
	v_lshl_add_u64 v[2:3], v[2:3], 0, s[34:35]
	s_addc_u32 s7, s9, s7
	s_lshl_b32 s34, s48, 10
	global_load_dword v99, v[2:3], off
	global_load_dword v98, v[2:3], off offset:16
	v_or_b32_e32 v2, s34, v93
	v_lshl_add_u32 v95, v2, 2, 0
	global_load_dword v100, v131, s[10:11]
	global_load_dword v97, v131, s[6:7]
	ds_read2st64_b32 v[30:31], v95 offset1:1
	ds_read2st64_b32 v[26:27], v95 offset0:128 offset1:129
	ds_read2st64_b32 v[28:29], v95 offset0:2 offset1:3
	ds_read2st64_b32 v[24:25], v95 offset0:4 offset1:5
	ds_read2st64_b32 v[22:23], v95 offset0:6 offset1:7
	ds_read2st64_b32 v[32:33], v95 offset0:130 offset1:131
	ds_read2st64_b32 v[20:21], v95 offset0:132 offset1:133
	ds_read2st64_b32 v[18:19], v95 offset0:134 offset1:135
	s_waitcnt lgkmcnt(6)
	v_pk_mul_f32 v[2:3], v[26:27], v[26:27]
	ds_read2st64_b32 v[14:15], v95 offset0:8 offset1:9
	ds_read2st64_b32 v[10:11], v95 offset0:136 offset1:137
	ds_read2st64_b32 v[12:13], v95 offset0:10 offset1:11
	ds_read2st64_b32 v[8:9], v95 offset0:12 offset1:13
	ds_read2st64_b32 v[6:7], v95 offset0:14 offset1:15
	v_add_f32_e32 v101, v2, v3
	s_waitcnt lgkmcnt(7)
	v_pk_mul_f32 v[2:3], v[32:33], v[32:33]
	v_mul_f32_e32 v96, v31, v31
	v_add_f32_e32 v105, v2, v3
	s_waitcnt lgkmcnt(6)
	v_pk_mul_f32 v[2:3], v[20:21], v[20:21]
	v_fmac_f32_e32 v96, v30, v30
	v_add_f32_e32 v107, v2, v3
	s_waitcnt lgkmcnt(5)
	v_pk_mul_f32 v[2:3], v[18:19], v[18:19]
	s_waitcnt lgkmcnt(3)
	v_pk_mul_f32 v[102:103], v[10:11], v[10:11]
	v_add_f32_e32 v109, v2, v3
	ds_read2st64_b32 v[16:17], v95 offset0:138 offset1:139
	ds_read2st64_b32 v[4:5], v95 offset0:140 offset1:141
	ds_read2st64_b32 v[2:3], v95 offset0:142 offset1:143
	v_add_f32_e32 v111, v102, v103
	s_waitcnt lgkmcnt(2)
	v_pk_mul_f32 v[102:103], v[16:17], v[16:17]
	v_mul_f32_e32 v104, v29, v29
	v_mul_f32_e32 v106, v25, v25
	v_mul_f32_e32 v108, v23, v23
	v_mul_f32_e32 v110, v15, v15
	v_mul_f32_e32 v112, v13, v13
	v_add_f32_e32 v113, v102, v103
	v_mul_f32_e32 v114, v9, v9
	s_waitcnt lgkmcnt(1)
	v_pk_mul_f32 v[102:103], v[4:5], v[4:5]
	v_mul_f32_e32 v116, v7, v7
	v_fmac_f32_e32 v104, v28, v28
	v_fmac_f32_e32 v106, v24, v24
	v_fmac_f32_e32 v108, v22, v22
	v_fmac_f32_e32 v110, v14, v14
	v_fmac_f32_e32 v112, v12, v12
	v_fmac_f32_e32 v114, v8, v8
	v_add_f32_e32 v115, v102, v103
	v_fmac_f32_e32 v116, v6, v6
	s_waitcnt lgkmcnt(0)
	v_pk_mul_f32 v[102:103], v[2:3], v[2:3]
	v_add_f32_e32 v102, v102, v103
	v_add_f32_dpp v96, v96, v96 row_ror:8 row_mask:0xf bank_mask:0xf
	v_add_f32_dpp v104, v104, v104 row_ror:8 row_mask:0xf bank_mask:0xf
	v_add_f32_dpp v106, v106, v106 row_ror:8 row_mask:0xf bank_mask:0xf
	v_add_f32_dpp v108, v108, v108 row_ror:8 row_mask:0xf bank_mask:0xf
	v_add_f32_dpp v110, v110, v110 row_ror:8 row_mask:0xf bank_mask:0xf
	v_add_f32_dpp v112, v112, v112 row_ror:8 row_mask:0xf bank_mask:0xf
	v_add_f32_dpp v114, v114, v114 row_ror:8 row_mask:0xf bank_mask:0xf
	v_add_f32_dpp v116, v116, v116 row_ror:8 row_mask:0xf bank_mask:0xf
	v_add_f32_dpp v96, v101, v101 row_ror:8 row_mask:0xf bank_mask:0xc
	v_add_f32_dpp v104, v105, v105 row_ror:8 row_mask:0xf bank_mask:0xc
	v_add_f32_dpp v106, v107, v107 row_ror:8 row_mask:0xf bank_mask:0xc
	v_add_f32_dpp v108, v109, v109 row_ror:8 row_mask:0xf bank_mask:0xc
	v_add_f32_dpp v110, v111, v111 row_ror:8 row_mask:0xf bank_mask:0xc
	v_add_f32_dpp v112, v113, v113 row_ror:8 row_mask:0xf bank_mask:0xc
	v_add_f32_dpp v114, v115, v115 row_ror:8 row_mask:0xf bank_mask:0xc
	v_add_f32_dpp v116, v102, v102 row_ror:8 row_mask:0xf bank_mask:0xc
	v_add_f32_dpp v96, v96, v96 row_ror:12 row_mask:0xf bank_mask:0xf
	v_add_f32_dpp v106, v106, v106 row_ror:12 row_mask:0xf bank_mask:0xf
	v_add_f32_dpp v110, v110, v110 row_ror:12 row_mask:0xf bank_mask:0xf
	v_add_f32_dpp v114, v114, v114 row_ror:12 row_mask:0xf bank_mask:0xf
	v_add_f32_dpp v96, v104, v104 row_ror:4 row_mask:0xf bank_mask:0xa
	v_add_f32_dpp v106, v108, v108 row_ror:4 row_mask:0xf bank_mask:0xa
	v_add_f32_dpp v110, v112, v112 row_ror:4 row_mask:0xf bank_mask:0xa
	v_add_f32_dpp v114, v116, v116 row_ror:4 row_mask:0xf bank_mask:0xa
	s_mov_b32 vcc_lo, 0xcccccccc
	s_mov_b32 vcc_hi, 0xcccccccc
	v_cndmask_b32_e32 v117, v96, v106, vcc
	v_cndmask_b32_e32 v118, v106, v96, vcc
	v_cndmask_b32_e32 v121, v110, v114, vcc
	v_cndmask_b32_e32 v122, v114, v110, vcc
	v_add_f32_dpp v96, v118, v117 quad_perm:[2,3,0,1] row_mask:0xf bank_mask:0xf
	s_nop 0
	v_add_f32_dpp v110, v122, v121 quad_perm:[2,3,0,1] row_mask:0xf bank_mask:0xf
	s_mov_b32 vcc_lo, 0xaaaaaaaa
	s_mov_b32 vcc_hi, 0xaaaaaaaa
	v_cndmask_b32_e32 v117, v96, v110, vcc
	v_cndmask_b32_e32 v118, v110, v96, vcc
	v_xor_b32_e32 v119, 32, v93
	s_nop 0
	v_add_f32_dpp v120, v118, v117 quad_perm:[1,0,3,2] row_mask:0xf bank_mask:0xf
	v_lshlrev_b32_e32 v119, 2, v119
	s_nop 1
	ds_swizzle_b32 v117, v120 offset:0x401f
	s_mov_b32 vcc_lo, 0xff00ff00
	s_mov_b32 vcc_hi, 0xff00ff00
	s_waitcnt lgkmcnt(0)
	v_add_f32_e32 v120, v120, v117
	s_nop 1
	ds_bpermute_b32 v117, v119, v120
	s_waitcnt lgkmcnt(0)
	v_add_f32_e32 v120, v120, v117
	v_add_f32_e32 v120, v120, v225
	v_rsq_f32_e32 v120, v120
	s_nop 0
	v_mul_f32_e32 v117, 0x3db504f3, v120
	v_cndmask_b32_e32 v120, v117, v120, vcc
	s_lshl_b32 vcc_hi, s48, 3
	v_readlane_b32 s7, v120, 0
	s_nop 1
	v_mov_b32_e32 v96, s7
	v_readlane_b32 s8, v120, 8
	v_mul_f32_e32 v30, v30, v96
	v_mul_f32_e32 v31, v31, v96
	v_readlane_b32 s9, v120, 4
	v_or_b32_e32 v101, 64, v93
	ds_write2st64_b32 v95, v30, v31 offset1:1
	v_cvt_pk_bf16_f32 v30, v30, s0
	v_readlane_b32 s10, v120, 12
	v_readlane_b32 s11, v120, 2
	v_readlane_b32 s40, v120, 6
	v_readlane_b32 s29, v120, 10
	v_readlane_b32 s41, v120, 14
	v_readlane_b32 s52, v120, 1
	v_readlane_b32 s53, v120, 9
	v_readlane_b32 s84, v120, 5
	v_readlane_b32 s85, v120, 13
	v_readlane_b32 vcc_lo, v120, 3
	v_readlane_b32 s28, v120, 11
	v_readlane_b32 s6, v120, 7
	v_readlane_b32 s7, v120, 15
	v_mov_b32_e32 v102, s8
	s_mul_i32 s8, s48, 0x440
	v_or_b32_e32 v218, s8, v93
	v_lshlrev_b32_e32 v218, 1, v218
	v_add_u32_e32 v218, s49, v218
	ds_write_b16 v218, v30
	v_cvt_pk_bf16_f32 v30, v31, s0
	ds_write_b16 v218, v30 offset:128
	v_mov_b32_e32 v30, s9
	v_mov_b32_e32 v103, s10
	v_mul_f32_e32 v104, v28, v30
	v_mul_f32_e32 v30, v29, v30
	v_mov_b32_e32 v28, v26
	v_mov_b32_e32 v29, v32
	v_pk_mul_f32 v[28:29], v[28:29], v[102:103]
	v_cvt_pk_bf16_f32 v26, v28, s0
	v_mov_b32_e32 v32, v27
	ds_write_b16 v218, v26 offset:17408
	v_pk_mul_f32 v[26:27], v[32:33], v[102:103]
	s_or_b32 s8, vcc_hi, 1
	v_cvt_pk_bf16_f32 v32, v26, s0
	ds_write_b16 v218, v32 offset:17536
	v_lshl_or_b32 v31, s8, 9, v94
	s_mulk_i32 s8, 0x88
	v_add_u32_e32 v31, 0, v31
	ds_write2st64_b32 v95, v28, v26 offset0:128 offset1:129
	ds_write2st64_b32 v31, v104, v30 offset1:1
	ds_write2st64_b32 v31, v29, v27 offset0:128 offset1:129
	v_cvt_pk_bf16_f32 v31, v104, s0
	ds_write_b16 v218, v31 offset:272
	v_cvt_pk_bf16_f32 v30, v30, s0
	ds_write_b16 v218, v30 offset:400
	v_cvt_pk_bf16_f32 v30, v29, s0
	ds_write_b16 v218, v30 offset:17680
	v_mov_b32_e32 v30, s11
	v_cvt_pk_bf16_f32 v32, v27, s0
	ds_write_b16 v218, v32 offset:17808
	v_mov_b32_e32 v31, v30
	v_mul_f32_e32 v24, v24, v31
	v_mul_f32_e32 v25, v25, v31
	v_lshl_or_b32 v31, s48, 12, v94
	s_add_i32 s9, s8, 0x88
	v_add_u32_e32 v32, 0, v31
	ds_write2st64_b32 v32, v24, v25 offset0:4 offset1:5
	v_cvt_pk_bf16_f32 v24, v24, s0
	ds_write_b16 v218, v24 offset:544
	v_cvt_pk_bf16_f32 v24, v25, s0
	v_mov_b32_e32 v94, s40
	v_mov_b32_e32 v30, s29
	ds_write_b16 v218, v24 offset:672
	v_mov_b32_e32 v31, s41
	v_mov_b32_e32 v33, v94
	v_mul_f32_e32 v94, v22, v33
	v_mul_f32_e32 v33, v23, v33
	v_mov_b32_e32 v22, v20
	v_mov_b32_e32 v23, v18
	v_pk_mul_f32 v[22:23], v[22:23], v[30:31]
	s_add_i32 s9, s8, 0x110
	v_cvt_pk_bf16_f32 v18, v22, s0
	ds_write_b16 v218, v18 offset:17952
	v_mov_b32_e32 v18, v21
	v_pk_mul_f32 v[18:19], v[18:19], v[30:31]
	v_cvt_pk_bf16_f32 v20, v18, s0
	ds_write2st64_b32 v32, v22, v18 offset0:132 offset1:133
	ds_write_b16 v218, v20 offset:18080
	ds_write2st64_b32 v32, v94, v33 offset0:6 offset1:7
	ds_write2st64_b32 v32, v23, v19 offset0:134 offset1:135
	v_cvt_pk_bf16_f32 v20, v94, s0
	ds_write_b16 v218, v20 offset:816
	v_cvt_pk_bf16_f32 v20, v33, s0
	ds_write_b16 v218, v20 offset:944
	v_cvt_pk_bf16_f32 v20, v23, s0
	ds_write_b16 v218, v20 offset:18224
	v_mov_b32_e32 v20, s52
	v_cvt_pk_bf16_f32 v21, v19, s0
	ds_write_b16 v218, v21 offset:18352
	v_mov_b32_e32 v21, v20
	s_add_i32 s9, s8, 0x198
	v_mul_f32_e32 v14, v14, v21
	v_mul_f32_e32 v15, v15, v21
	ds_write2st64_b32 v32, v14, v15 offset0:8 offset1:9
	v_cvt_pk_bf16_f32 v14, v14, s0
	ds_write_b16 v218, v14 offset:1088
	v_cvt_pk_bf16_f32 v14, v15, s0
	v_mov_b32_e32 v25, s84
	v_mov_b32_e32 v20, s53
	ds_write_b16 v218, v14 offset:1216
	v_mov_b32_e32 v21, s85
	v_mov_b32_e32 v24, v25
	v_mul_f32_e32 v25, v12, v24
	v_mul_f32_e32 v24, v13, v24
	v_mov_b32_e32 v12, v10
	v_mov_b32_e32 v13, v16
	v_pk_mul_f32 v[12:13], v[12:13], v[20:21]
	v_mov_b32_e32 v16, v11
	v_cvt_pk_bf16_f32 v10, v12, s0
	ds_write_b16 v218, v10 offset:18496
	v_pk_mul_f32 v[10:11], v[16:17], v[20:21]
	v_cvt_pk_bf16_f32 v14, v10, s0
	s_add_i32 s9, s8, 0x220
	ds_write2st64_b32 v32, v12, v10 offset0:136 offset1:137
	ds_write_b16 v218, v14 offset:18624
	ds_write2st64_b32 v32, v25, v24 offset0:10 offset1:11
	ds_write2st64_b32 v32, v13, v11 offset0:138 offset1:139
	v_cvt_pk_bf16_f32 v14, v25, s0
	ds_write_b16 v218, v14 offset:1360
	v_cvt_pk_bf16_f32 v14, v24, s0
	ds_write_b16 v218, v14 offset:1488
	v_cvt_pk_bf16_f32 v14, v13, s0
	ds_write_b16 v218, v14 offset:18768
	v_mov_b32_e32 v14, vcc_lo
	v_cvt_pk_bf16_f32 v15, v11, s0
	ds_write_b16 v218, v15 offset:18896
	v_mov_b32_e32 v15, v14
	s_add_i32 s9, s8, 0x2a8
	v_mul_f32_e32 v8, v8, v15
	v_mul_f32_e32 v9, v9, v15
	ds_write2st64_b32 v32, v8, v9 offset0:12 offset1:13
	v_cvt_pk_bf16_f32 v8, v8, s0
	ds_write_b16 v218, v8 offset:1632
	v_cvt_pk_bf16_f32 v8, v9, s0
	v_mov_b32_e32 v17, s6
	v_mov_b32_e32 v14, s28
	ds_write_b16 v218, v8 offset:1760
	v_mov_b32_e32 v15, s7
	v_mov_b32_e32 v9, v17
	v_mul_f32_e32 v17, v6, v9
	v_mul_f32_e32 v20, v7, v9
	v_mov_b32_e32 v6, v4
	v_mov_b32_e32 v7, v2
	v_pk_mul_f32 v[6:7], v[6:7], v[14:15]
	s_addk_i32 s8, 0x330
	v_cvt_pk_bf16_f32 v2, v6, s0
	ds_write_b16 v218, v2 offset:19040
	v_mov_b32_e32 v2, v5
	v_pk_mul_f32 v[8:9], v[2:3], v[14:15]
	v_cvt_pk_bf16_f32 v2, v8, s0
	ds_write2st64_b32 v32, v6, v8 offset0:140 offset1:141
	ds_write_b16 v218, v2 offset:19168
	ds_write2st64_b32 v32, v17, v20 offset0:14 offset1:15
	ds_write2st64_b32 v32, v7, v9 offset0:142 offset1:143
	v_cvt_pk_bf16_f32 v2, v17, s0
	ds_write_b16 v218, v2 offset:1904
	v_cvt_pk_bf16_f32 v2, v20, s0
	ds_write_b16 v218, v2 offset:2032
	v_cvt_pk_bf16_f32 v5, v6, v7
	v_bitop3_b32 v6, s48, v1, 7 bitop3:0x78
	v_cvt_pk_bf16_f32 v2, v7, s0
	v_lshlrev_b32_e32 v7, 7, v93
	s_add_i32 s6, 0, 0x14000
	v_lshlrev_b32_e32 v6, 4, v6
	s_ashr_i32 s53, s48, 1
	v_add3_u32 v6, s6, v7, v6
	s_and_b32 s6, s53, 1
	s_and_b32 s52, s48, 1
	s_cmp_eq_u32 s6, 0
	ds_write_b16 v218, v2 offset:19312
	v_cvt_pk_bf16_f32 v2, v9, s0
	s_cselect_b64 s[8:9], -1, 0
	s_bitcmp1_b32 s48, 0
	ds_write_b16 v218, v2 offset:19440
	v_cvt_pk_bf16_f32 v4, v12, v13
	v_cvt_pk_bf16_f32 v3, v22, v23
	v_cvt_pk_bf16_f32 v2, v28, v29
	s_cselect_b64 s[10:11], -1, 0
	ds_write_b128 v6, v[2:5]
	v_cvt_pk_bf16_f32 v5, v8, v9
	v_cvt_pk_bf16_f32 v4, v10, v11
	v_cvt_pk_bf16_f32 v3, v18, v19
	v_cvt_pk_bf16_f32 v2, v26, v27
	s_and_b64 s[8:9], s[8:9], s[10:11]
	ds_write_b128 v6, v[2:5] offset:8192
	v_and_b32_e32 v94, 31, v1
	v_lshrrev_b32_e32 v95, 5, v93
	v_mov_b32_e32 v2, 0
	s_and_b64 vcc, exec, s[8:9]
	v_mov_b32_e32 v3, 0
	v_mov_b32_e32 v4, 0
	v_mov_b32_e32 v5, 0
	v_mov_b32_e32 v6, 0
	v_mov_b32_e32 v7, 0
	v_mov_b32_e32 v8, 0
	v_mov_b32_e32 v9, 0
	v_mov_b32_e32 v10, 0
	v_mov_b32_e32 v11, 0
	v_mov_b32_e32 v12, 0
	v_mov_b32_e32 v13, 0
	v_mov_b32_e32 v14, 0
	v_mov_b32_e32 v15, 0
	v_mov_b32_e32 v16, 0
	v_mov_b32_e32 v17, 0
	s_waitcnt lgkmcnt(0)
	s_barrier
	s_cbranch_vccz .LBB0_136
	s_cmp_gt_u32 s48, 3
	v_lshlrev_b32_e32 v25, 2, v95
	s_mov_b64 s[28:29], -1
	s_cbranch_scc1 .LBB0_137
